# speedup vs baseline: 1.0354x; 1.0218x over previous
; __global__ void __launch_bounds__(512, 2) fwd_megakernel(Args a) {
;     ...
;             for (int tile = blk; tile < M / 32; tile += G) {
;                 const int m0 = tile * 32;
;                 f32x4 acc2[2];
; #pragma unroll
;                 for (int mt = 0; mt < 2; ++mt) acc2[mt] = (f32x4){0.f, 0.f, 0.f, 0.f};
;                 const u16* bp = WX + (size_t)(16 * wave + lq) * DM + 8 * lg;
;                 const u16* ap0 = XN + (size_t)(m0 + lq) * DM + 8 * lg; const u16* ap1 = ap0 + (size_t)16 * DM;
; #pragma unroll 16
;                 for (int ks = 0; ks < DM / 32; ++ks) {
;                     const bf16x8 bv = *(const bf16x8*)(bp + 32 * ks);
;                     const bf16x8 av0 = *(const bf16x8*)(ap0 + 32 * ks), av1 = *(const bf16x8*)(ap1 + 32 * ks);
;                     acc2[0] = __builtin_amdgcn_mfma_f32_16x16x32_bf16(av0, bv, acc2[0], 0, 0, 0);
;                     acc2[1] = __builtin_amdgcn_mfma_f32_16x16x32_bf16(av1, bv, acc2[1], 0, 0, 0);
;                 }
; #pragma unroll
;                 for (int mt = 0; mt < 2; ++mt)
; #pragma unroll
;                     for (int j = 0; j < 4; ++j) XWXA[(size_t)(m0 + 16 * mt + 4 * lg + j) * 128 + 16 * wave + lq] = acc2[mt][j];
.LBB0_133:
	s_add_u32 s0, s88, 0xab00000
	s_addc_u32 s1, s89, 0
	v_lshrrev_b32_e32 v202, 4, v225
	s_cmpk_lt_i32 s97, 0x100
	s_cselect_b64 s[4:5], -1, 0
	s_cmpk_gt_i32 s97, 0xff
	v_lshlrev_b32_e32 v201, 2, v202
	v_lshlrev_b32_e32 v164, 2, v162
	v_and_b32_e32 v138, 48, v218
	s_cbranch_scc1 .LBB0_138
	v_mov_b32_e32 v165, 0
	v_mov_b32_e32 v139, 0
	v_readlane_b32 s6, v252, 14
	v_readlane_b32 s14, v252, 6
	v_readlane_b32 s15, v252, 7
	v_lshl_or_b32 v226, v162, 12, v138
	v_lshl_add_u32 v227, v201, 9, v164
	v_add_u32_e32 v228, 0x2000, v227
	v_mul_u32_u24_e32 v229, 4112, v162
	v_add_u32_e32 v229, v229, v138
	v_add_u32_e32 v230, 65792, v229
	v_lshlrev_b32_e32 v232, 4, v225
	v_mov_b32_e32 v233, 0
	s_lshl_b32 s2, s6, 16
	s_add_u32 s8, s88, 0xff80000
	s_addc_u32 s9, s89, 0
	s_add_u32 s8, s8, s2
	s_addc_u32 s9, s9, 0
	s_lshl_b32 s2, s6, 6
	s_add_u32 s10, s0, s2
	s_addc_u32 s11, s1, 0
	s_mul_i32 s7, s6, 16448
	s_lshl_b32 s6, s6, 14
	s_mov_b32 s3, s97
.Lxw_tile:
	s_lshl_b32 s2, s3, 17
	s_add_u32 s12, s14, s2
	s_addc_u32 s13, s15, 0
	s_add_u32 s12, s12, s6
	s_addc_u32 s13, s13, 0
	v_lshl_add_u64 v[234:235], s[12:13], 0, v[232:233]
	s_add_i32 m0, s7, 0
	s_nop 0
	global_load_lds_dwordx4 v[234:235], off
	global_load_lds_dwordx4 v[234:235], off offset:1024
	global_load_lds_dwordx4 v[234:235], off offset:2048
	global_load_lds_dwordx4 v[234:235], off offset:3072
	v_add_co_u32_e32 v234, vcc, 0x1000, v234
	s_nop 1
	v_addc_co_u32_e32 v235, vcc, 0, v235, vcc
	s_add_i32 m0, s7, 4112
	s_nop 0
	global_load_lds_dwordx4 v[234:235], off
	global_load_lds_dwordx4 v[234:235], off offset:1024
	global_load_lds_dwordx4 v[234:235], off offset:2048
	global_load_lds_dwordx4 v[234:235], off offset:3072
	v_add_co_u32_e32 v234, vcc, 0x1000, v234
	s_nop 1
	v_addc_co_u32_e32 v235, vcc, 0, v235, vcc
	s_add_i32 m0, s7, 8224
	s_nop 0
	global_load_lds_dwordx4 v[234:235], off
	global_load_lds_dwordx4 v[234:235], off offset:1024
	global_load_lds_dwordx4 v[234:235], off offset:2048
	global_load_lds_dwordx4 v[234:235], off offset:3072
	v_add_co_u32_e32 v234, vcc, 0x1000, v234
	s_nop 1
	v_addc_co_u32_e32 v235, vcc, 0, v235, vcc
	s_add_i32 m0, s7, 12336
	s_nop 0
	global_load_lds_dwordx4 v[234:235], off
	global_load_lds_dwordx4 v[234:235], off offset:1024
	global_load_lds_dwordx4 v[234:235], off offset:2048
	global_load_lds_dwordx4 v[234:235], off offset:3072
	s_lshl_b32 s2, s3, 14
	s_add_u32 s12, s10, s2
	s_addc_u32 s13, s11, 0
	v_mov_b32_e32 v208, 0
	v_mov_b32_e32 v209, 0
	v_mov_b32_e32 v210, 0
	v_mov_b32_e32 v211, 0
	v_mov_b32_e32 v212, 0
	v_mov_b32_e32 v213, 0
	v_mov_b32_e32 v214, 0
	v_mov_b32_e32 v215, 0
	global_load_dwordx4 v[0:3], v226, s[8:9]
	global_load_dwordx4 v[4:7], v226, s[8:9] offset:64
	global_load_dwordx4 v[8:11], v226, s[8:9] offset:128
	global_load_dwordx4 v[12:15], v226, s[8:9] offset:192
	global_load_dwordx4 v[16:19], v226, s[8:9] offset:256
	global_load_dwordx4 v[20:23], v226, s[8:9] offset:320
	global_load_dwordx4 v[24:27], v226, s[8:9] offset:384
	global_load_dwordx4 v[28:31], v226, s[8:9] offset:448
	global_load_dwordx4 v[32:35], v226, s[8:9] offset:512
	global_load_dwordx4 v[36:39], v226, s[8:9] offset:576
	global_load_dwordx4 v[40:43], v226, s[8:9] offset:640
	global_load_dwordx4 v[44:47], v226, s[8:9] offset:704
	global_load_dwordx4 v[48:51], v226, s[8:9] offset:768
	global_load_dwordx4 v[52:55], v226, s[8:9] offset:832
	global_load_dwordx4 v[56:59], v226, s[8:9] offset:896
	global_load_dwordx4 v[60:63], v226, s[8:9] offset:960
	s_waitcnt vmcnt(16)
	s_barrier
	ds_read_b128 v[64:67], v229
	ds_read_b128 v[68:71], v230
	ds_read_b128 v[72:75], v229 offset:64
	ds_read_b128 v[76:79], v230 offset:64
	ds_read_b128 v[80:83], v229 offset:128
	ds_read_b128 v[84:87], v230 offset:128
	s_waitcnt vmcnt(15) lgkmcnt(4)
	v_mfma_f32_16x16x32_bf16 v[208:211], v[64:67], v[0:3], v[208:211]
	v_mfma_f32_16x16x32_bf16 v[212:215], v[68:71], v[0:3], v[212:215]
	global_load_dwordx4 v[0:3], v226, s[8:9] offset:1024
	ds_read_b128 v[64:67], v229 offset:192
	ds_read_b128 v[68:71], v230 offset:192
	s_waitcnt vmcnt(15) lgkmcnt(4)
	v_mfma_f32_16x16x32_bf16 v[208:211], v[72:75], v[4:7], v[208:211]
	v_mfma_f32_16x16x32_bf16 v[212:215], v[76:79], v[4:7], v[212:215]
	global_load_dwordx4 v[4:7], v226, s[8:9] offset:1088
	ds_read_b128 v[72:75], v229 offset:256
	ds_read_b128 v[76:79], v230 offset:256
	s_waitcnt vmcnt(15) lgkmcnt(4)
	v_mfma_f32_16x16x32_bf16 v[208:211], v[80:83], v[8:11], v[208:211]
	v_mfma_f32_16x16x32_bf16 v[212:215], v[84:87], v[8:11], v[212:215]
	global_load_dwordx4 v[8:11], v226, s[8:9] offset:1152
	ds_read_b128 v[80:83], v229 offset:320
	ds_read_b128 v[84:87], v230 offset:320
	s_waitcnt vmcnt(15) lgkmcnt(4)
	v_mfma_f32_16x16x32_bf16 v[208:211], v[64:67], v[12:15], v[208:211]
	v_mfma_f32_16x16x32_bf16 v[212:215], v[68:71], v[12:15], v[212:215]
	global_load_dwordx4 v[12:15], v226, s[8:9] offset:1216
	ds_read_b128 v[64:67], v229 offset:384
	ds_read_b128 v[68:71], v230 offset:384
	s_waitcnt vmcnt(15) lgkmcnt(4)
	v_mfma_f32_16x16x32_bf16 v[208:211], v[72:75], v[16:19], v[208:211]
	v_mfma_f32_16x16x32_bf16 v[212:215], v[76:79], v[16:19], v[212:215]
	global_load_dwordx4 v[16:19], v226, s[8:9] offset:1280
	ds_read_b128 v[72:75], v229 offset:448
	ds_read_b128 v[76:79], v230 offset:448
	s_waitcnt vmcnt(15) lgkmcnt(4)
	v_mfma_f32_16x16x32_bf16 v[208:211], v[80:83], v[20:23], v[208:211]
	v_mfma_f32_16x16x32_bf16 v[212:215], v[84:87], v[20:23], v[212:215]
	global_load_dwordx4 v[20:23], v226, s[8:9] offset:1344
	ds_read_b128 v[80:83], v229 offset:512
	ds_read_b128 v[84:87], v230 offset:512
	s_waitcnt vmcnt(15) lgkmcnt(4)
; __global__ void __launch_bounds__(512, 2) fwd_megakernel(Args a) {
;     ...
;                 for (int ks = 0; ks < DM / 32; ++ks) {
;                     const bf16x8 bv = *(const bf16x8*)(bp + 32 * ks);
;                     const bf16x8 av0 = *(const bf16x8*)(ap0 + 32 * ks), av1 = *(const bf16x8*)(ap1 + 32 * ks);
;                     acc2[0] = __builtin_amdgcn_mfma_f32_16x16x32_bf16(av0, bv, acc2[0], 0, 0, 0);
;                     acc2[1] = __builtin_amdgcn_mfma_f32_16x16x32_bf16(av1, bv, acc2[1], 0, 0, 0);
;                 }
	v_mfma_f32_16x16x32_bf16 v[208:211], v[64:67], v[24:27], v[208:211]
	v_mfma_f32_16x16x32_bf16 v[212:215], v[68:71], v[24:27], v[212:215]
	global_load_dwordx4 v[24:27], v226, s[8:9] offset:1408
	ds_read_b128 v[64:67], v229 offset:576
	ds_read_b128 v[68:71], v230 offset:576
	s_waitcnt vmcnt(15) lgkmcnt(4)
	v_mfma_f32_16x16x32_bf16 v[208:211], v[72:75], v[28:31], v[208:211]
	v_mfma_f32_16x16x32_bf16 v[212:215], v[76:79], v[28:31], v[212:215]
	global_load_dwordx4 v[28:31], v226, s[8:9] offset:1472
	ds_read_b128 v[72:75], v229 offset:640
	ds_read_b128 v[76:79], v230 offset:640
	s_waitcnt vmcnt(15) lgkmcnt(4)
	v_mfma_f32_16x16x32_bf16 v[208:211], v[80:83], v[32:35], v[208:211]
	v_mfma_f32_16x16x32_bf16 v[212:215], v[84:87], v[32:35], v[212:215]
	global_load_dwordx4 v[32:35], v226, s[8:9] offset:1536
	ds_read_b128 v[80:83], v229 offset:704
	ds_read_b128 v[84:87], v230 offset:704
	s_waitcnt vmcnt(15) lgkmcnt(4)
	v_mfma_f32_16x16x32_bf16 v[208:211], v[64:67], v[36:39], v[208:211]
	v_mfma_f32_16x16x32_bf16 v[212:215], v[68:71], v[36:39], v[212:215]
	global_load_dwordx4 v[36:39], v226, s[8:9] offset:1600
	ds_read_b128 v[64:67], v229 offset:768
	ds_read_b128 v[68:71], v230 offset:768
	s_waitcnt vmcnt(15) lgkmcnt(4)
	v_mfma_f32_16x16x32_bf16 v[208:211], v[72:75], v[40:43], v[208:211]
	v_mfma_f32_16x16x32_bf16 v[212:215], v[76:79], v[40:43], v[212:215]
	global_load_dwordx4 v[40:43], v226, s[8:9] offset:1664
	ds_read_b128 v[72:75], v229 offset:832
	ds_read_b128 v[76:79], v230 offset:832
	s_waitcnt vmcnt(15) lgkmcnt(4)
	v_mfma_f32_16x16x32_bf16 v[208:211], v[80:83], v[44:47], v[208:211]
	v_mfma_f32_16x16x32_bf16 v[212:215], v[84:87], v[44:47], v[212:215]
	global_load_dwordx4 v[44:47], v226, s[8:9] offset:1728
	ds_read_b128 v[80:83], v229 offset:896
	ds_read_b128 v[84:87], v230 offset:896
	s_waitcnt vmcnt(15) lgkmcnt(4)
	v_mfma_f32_16x16x32_bf16 v[208:211], v[64:67], v[48:51], v[208:211]
	v_mfma_f32_16x16x32_bf16 v[212:215], v[68:71], v[48:51], v[212:215]
	global_load_dwordx4 v[48:51], v226, s[8:9] offset:1792
	ds_read_b128 v[64:67], v229 offset:960
	ds_read_b128 v[68:71], v230 offset:960
	s_waitcnt vmcnt(15) lgkmcnt(4)
	v_mfma_f32_16x16x32_bf16 v[208:211], v[72:75], v[52:55], v[208:211]
	v_mfma_f32_16x16x32_bf16 v[212:215], v[76:79], v[52:55], v[212:215]
	global_load_dwordx4 v[52:55], v226, s[8:9] offset:1856
	ds_read_b128 v[72:75], v229 offset:1024
	ds_read_b128 v[76:79], v230 offset:1024
	s_waitcnt vmcnt(15) lgkmcnt(4)
	v_mfma_f32_16x16x32_bf16 v[208:211], v[80:83], v[56:59], v[208:211]
	v_mfma_f32_16x16x32_bf16 v[212:215], v[84:87], v[56:59], v[212:215]
	global_load_dwordx4 v[56:59], v226, s[8:9] offset:1920
	ds_read_b128 v[80:83], v229 offset:1088
	ds_read_b128 v[84:87], v230 offset:1088
	s_waitcnt vmcnt(15) lgkmcnt(4)
	v_mfma_f32_16x16x32_bf16 v[208:211], v[64:67], v[60:63], v[208:211]
	v_mfma_f32_16x16x32_bf16 v[212:215], v[68:71], v[60:63], v[212:215]
	global_load_dwordx4 v[60:63], v226, s[8:9] offset:1984
	ds_read_b128 v[64:67], v229 offset:1152
	ds_read_b128 v[68:71], v230 offset:1152
	s_waitcnt vmcnt(15) lgkmcnt(4)
	v_mfma_f32_16x16x32_bf16 v[208:211], v[72:75], v[0:3], v[208:211]
	v_mfma_f32_16x16x32_bf16 v[212:215], v[76:79], v[0:3], v[212:215]
	global_load_dwordx4 v[0:3], v226, s[8:9] offset:2048
	ds_read_b128 v[72:75], v229 offset:1216
	ds_read_b128 v[76:79], v230 offset:1216
	s_waitcnt vmcnt(15) lgkmcnt(4)
	v_mfma_f32_16x16x32_bf16 v[208:211], v[80:83], v[4:7], v[208:211]
	v_mfma_f32_16x16x32_bf16 v[212:215], v[84:87], v[4:7], v[212:215]
	global_load_dwordx4 v[4:7], v226, s[8:9] offset:2112
	ds_read_b128 v[80:83], v229 offset:1280
	ds_read_b128 v[84:87], v230 offset:1280
	s_waitcnt vmcnt(15) lgkmcnt(4)
	v_mfma_f32_16x16x32_bf16 v[208:211], v[64:67], v[8:11], v[208:211]
	v_mfma_f32_16x16x32_bf16 v[212:215], v[68:71], v[8:11], v[212:215]
	global_load_dwordx4 v[8:11], v226, s[8:9] offset:2176
	ds_read_b128 v[64:67], v229 offset:1344
	ds_read_b128 v[68:71], v230 offset:1344
	s_waitcnt vmcnt(15) lgkmcnt(4)
	v_mfma_f32_16x16x32_bf16 v[208:211], v[72:75], v[12:15], v[208:211]
	v_mfma_f32_16x16x32_bf16 v[212:215], v[76:79], v[12:15], v[212:215]
	global_load_dwordx4 v[12:15], v226, s[8:9] offset:2240
	ds_read_b128 v[72:75], v229 offset:1408
	ds_read_b128 v[76:79], v230 offset:1408
	s_waitcnt vmcnt(15) lgkmcnt(4)
	v_mfma_f32_16x16x32_bf16 v[208:211], v[80:83], v[16:19], v[208:211]
	v_mfma_f32_16x16x32_bf16 v[212:215], v[84:87], v[16:19], v[212:215]
	global_load_dwordx4 v[16:19], v226, s[8:9] offset:2304
	ds_read_b128 v[80:83], v229 offset:1472
	ds_read_b128 v[84:87], v230 offset:1472
	s_waitcnt vmcnt(15) lgkmcnt(4)
	v_mfma_f32_16x16x32_bf16 v[208:211], v[64:67], v[20:23], v[208:211]
	v_mfma_f32_16x16x32_bf16 v[212:215], v[68:71], v[20:23], v[212:215]
	global_load_dwordx4 v[20:23], v226, s[8:9] offset:2368
	ds_read_b128 v[64:67], v229 offset:1536
	ds_read_b128 v[68:71], v230 offset:1536
	s_waitcnt vmcnt(15) lgkmcnt(4)
	v_mfma_f32_16x16x32_bf16 v[208:211], v[72:75], v[24:27], v[208:211]
	v_mfma_f32_16x16x32_bf16 v[212:215], v[76:79], v[24:27], v[212:215]
	global_load_dwordx4 v[24:27], v226, s[8:9] offset:2432
	ds_read_b128 v[72:75], v229 offset:1600
	ds_read_b128 v[76:79], v230 offset:1600
	s_waitcnt vmcnt(15) lgkmcnt(4)
	v_mfma_f32_16x16x32_bf16 v[208:211], v[80:83], v[28:31], v[208:211]
	v_mfma_f32_16x16x32_bf16 v[212:215], v[84:87], v[28:31], v[212:215]
	global_load_dwordx4 v[28:31], v226, s[8:9] offset:2496
	ds_read_b128 v[80:83], v229 offset:1664
	ds_read_b128 v[84:87], v230 offset:1664
	s_waitcnt vmcnt(15) lgkmcnt(4)
; __global__ void __launch_bounds__(512, 2) fwd_megakernel(Args a) {
;     ...
;                 for (int ks = 0; ks < DM / 32; ++ks) {
;                     const bf16x8 bv = *(const bf16x8*)(bp + 32 * ks);
;                     const bf16x8 av0 = *(const bf16x8*)(ap0 + 32 * ks), av1 = *(const bf16x8*)(ap1 + 32 * ks);
;                     acc2[0] = __builtin_amdgcn_mfma_f32_16x16x32_bf16(av0, bv, acc2[0], 0, 0, 0);
;                     acc2[1] = __builtin_amdgcn_mfma_f32_16x16x32_bf16(av1, bv, acc2[1], 0, 0, 0);
;                 }
	v_mfma_f32_16x16x32_bf16 v[208:211], v[64:67], v[32:35], v[208:211]
	v_mfma_f32_16x16x32_bf16 v[212:215], v[68:71], v[32:35], v[212:215]
	global_load_dwordx4 v[32:35], v226, s[8:9] offset:2560
	ds_read_b128 v[64:67], v229 offset:1728
	ds_read_b128 v[68:71], v230 offset:1728
	s_waitcnt vmcnt(15) lgkmcnt(4)
	v_mfma_f32_16x16x32_bf16 v[208:211], v[72:75], v[36:39], v[208:211]
	v_mfma_f32_16x16x32_bf16 v[212:215], v[76:79], v[36:39], v[212:215]
	global_load_dwordx4 v[36:39], v226, s[8:9] offset:2624
	ds_read_b128 v[72:75], v229 offset:1792
	ds_read_b128 v[76:79], v230 offset:1792
	s_waitcnt vmcnt(15) lgkmcnt(4)
	v_mfma_f32_16x16x32_bf16 v[208:211], v[80:83], v[40:43], v[208:211]
	v_mfma_f32_16x16x32_bf16 v[212:215], v[84:87], v[40:43], v[212:215]
	global_load_dwordx4 v[40:43], v226, s[8:9] offset:2688
	ds_read_b128 v[80:83], v229 offset:1856
	ds_read_b128 v[84:87], v230 offset:1856
	s_waitcnt vmcnt(15) lgkmcnt(4)
	v_mfma_f32_16x16x32_bf16 v[208:211], v[64:67], v[44:47], v[208:211]
	v_mfma_f32_16x16x32_bf16 v[212:215], v[68:71], v[44:47], v[212:215]
	global_load_dwordx4 v[44:47], v226, s[8:9] offset:2752
	ds_read_b128 v[64:67], v229 offset:1920
	ds_read_b128 v[68:71], v230 offset:1920
	s_waitcnt vmcnt(15) lgkmcnt(4)
	v_mfma_f32_16x16x32_bf16 v[208:211], v[72:75], v[48:51], v[208:211]
	v_mfma_f32_16x16x32_bf16 v[212:215], v[76:79], v[48:51], v[212:215]
	global_load_dwordx4 v[48:51], v226, s[8:9] offset:2816
	ds_read_b128 v[72:75], v229 offset:1984
	ds_read_b128 v[76:79], v230 offset:1984
	s_waitcnt vmcnt(15) lgkmcnt(4)
	v_mfma_f32_16x16x32_bf16 v[208:211], v[80:83], v[52:55], v[208:211]
	v_mfma_f32_16x16x32_bf16 v[212:215], v[84:87], v[52:55], v[212:215]
	global_load_dwordx4 v[52:55], v226, s[8:9] offset:2880
	ds_read_b128 v[80:83], v229 offset:2048
	ds_read_b128 v[84:87], v230 offset:2048
	s_waitcnt vmcnt(15) lgkmcnt(4)
	v_mfma_f32_16x16x32_bf16 v[208:211], v[64:67], v[56:59], v[208:211]
	v_mfma_f32_16x16x32_bf16 v[212:215], v[68:71], v[56:59], v[212:215]
	global_load_dwordx4 v[56:59], v226, s[8:9] offset:2944
	ds_read_b128 v[64:67], v229 offset:2112
	ds_read_b128 v[68:71], v230 offset:2112
	s_waitcnt vmcnt(15) lgkmcnt(4)
	v_mfma_f32_16x16x32_bf16 v[208:211], v[72:75], v[60:63], v[208:211]
	v_mfma_f32_16x16x32_bf16 v[212:215], v[76:79], v[60:63], v[212:215]
	global_load_dwordx4 v[60:63], v226, s[8:9] offset:3008
	ds_read_b128 v[72:75], v229 offset:2176
	ds_read_b128 v[76:79], v230 offset:2176
	s_waitcnt vmcnt(15) lgkmcnt(4)
	v_mfma_f32_16x16x32_bf16 v[208:211], v[80:83], v[0:3], v[208:211]
	v_mfma_f32_16x16x32_bf16 v[212:215], v[84:87], v[0:3], v[212:215]
	global_load_dwordx4 v[0:3], v226, s[8:9] offset:3072
	ds_read_b128 v[80:83], v229 offset:2240
	ds_read_b128 v[84:87], v230 offset:2240
	s_waitcnt vmcnt(15) lgkmcnt(4)
	v_mfma_f32_16x16x32_bf16 v[208:211], v[64:67], v[4:7], v[208:211]
	v_mfma_f32_16x16x32_bf16 v[212:215], v[68:71], v[4:7], v[212:215]
	global_load_dwordx4 v[4:7], v226, s[8:9] offset:3136
	ds_read_b128 v[64:67], v229 offset:2304
	ds_read_b128 v[68:71], v230 offset:2304
	s_waitcnt vmcnt(15) lgkmcnt(4)
	v_mfma_f32_16x16x32_bf16 v[208:211], v[72:75], v[8:11], v[208:211]
	v_mfma_f32_16x16x32_bf16 v[212:215], v[76:79], v[8:11], v[212:215]
	global_load_dwordx4 v[8:11], v226, s[8:9] offset:3200
	ds_read_b128 v[72:75], v229 offset:2368
	ds_read_b128 v[76:79], v230 offset:2368
	s_waitcnt vmcnt(15) lgkmcnt(4)
	v_mfma_f32_16x16x32_bf16 v[208:211], v[80:83], v[12:15], v[208:211]
	v_mfma_f32_16x16x32_bf16 v[212:215], v[84:87], v[12:15], v[212:215]
	global_load_dwordx4 v[12:15], v226, s[8:9] offset:3264
	ds_read_b128 v[80:83], v229 offset:2432
	ds_read_b128 v[84:87], v230 offset:2432
	s_waitcnt vmcnt(15) lgkmcnt(4)
	v_mfma_f32_16x16x32_bf16 v[208:211], v[64:67], v[16:19], v[208:211]
	v_mfma_f32_16x16x32_bf16 v[212:215], v[68:71], v[16:19], v[212:215]
	global_load_dwordx4 v[16:19], v226, s[8:9] offset:3328
	ds_read_b128 v[64:67], v229 offset:2496
	ds_read_b128 v[68:71], v230 offset:2496
	s_waitcnt vmcnt(15) lgkmcnt(4)
	v_mfma_f32_16x16x32_bf16 v[208:211], v[72:75], v[20:23], v[208:211]
	v_mfma_f32_16x16x32_bf16 v[212:215], v[76:79], v[20:23], v[212:215]
	global_load_dwordx4 v[20:23], v226, s[8:9] offset:3392
	ds_read_b128 v[72:75], v229 offset:2560
	ds_read_b128 v[76:79], v230 offset:2560
	s_waitcnt vmcnt(15) lgkmcnt(4)
	v_mfma_f32_16x16x32_bf16 v[208:211], v[80:83], v[24:27], v[208:211]
	v_mfma_f32_16x16x32_bf16 v[212:215], v[84:87], v[24:27], v[212:215]
	global_load_dwordx4 v[24:27], v226, s[8:9] offset:3456
	ds_read_b128 v[80:83], v229 offset:2624
	ds_read_b128 v[84:87], v230 offset:2624
	s_waitcnt vmcnt(15) lgkmcnt(4)
	v_mfma_f32_16x16x32_bf16 v[208:211], v[64:67], v[28:31], v[208:211]
	v_mfma_f32_16x16x32_bf16 v[212:215], v[68:71], v[28:31], v[212:215]
	global_load_dwordx4 v[28:31], v226, s[8:9] offset:3520
	ds_read_b128 v[64:67], v229 offset:2688
	ds_read_b128 v[68:71], v230 offset:2688
	s_waitcnt vmcnt(15) lgkmcnt(4)
	v_mfma_f32_16x16x32_bf16 v[208:211], v[72:75], v[32:35], v[208:211]
	v_mfma_f32_16x16x32_bf16 v[212:215], v[76:79], v[32:35], v[212:215]
	global_load_dwordx4 v[32:35], v226, s[8:9] offset:3584
	ds_read_b128 v[72:75], v229 offset:2752
	ds_read_b128 v[76:79], v230 offset:2752
	s_waitcnt vmcnt(15) lgkmcnt(4)
	v_mfma_f32_16x16x32_bf16 v[208:211], v[80:83], v[36:39], v[208:211]
	v_mfma_f32_16x16x32_bf16 v[212:215], v[84:87], v[36:39], v[212:215]
	global_load_dwordx4 v[36:39], v226, s[8:9] offset:3648
	ds_read_b128 v[80:83], v229 offset:2816
	ds_read_b128 v[84:87], v230 offset:2816
	s_waitcnt vmcnt(15) lgkmcnt(4)
; __global__ void __launch_bounds__(512, 2) fwd_megakernel(Args a) {
;     ...
;                 for (int ks = 0; ks < DM / 32; ++ks) {
;                     const bf16x8 bv = *(const bf16x8*)(bp + 32 * ks);
;                     const bf16x8 av0 = *(const bf16x8*)(ap0 + 32 * ks), av1 = *(const bf16x8*)(ap1 + 32 * ks);
;                     acc2[0] = __builtin_amdgcn_mfma_f32_16x16x32_bf16(av0, bv, acc2[0], 0, 0, 0);
;                     acc2[1] = __builtin_amdgcn_mfma_f32_16x16x32_bf16(av1, bv, acc2[1], 0, 0, 0);
;                 }
; #pragma unroll
;                 for (int mt = 0; mt < 2; ++mt)
; #pragma unroll
;                     for (int j = 0; j < 4; ++j) XWXA[(size_t)(m0 + 16 * mt + 4 * lg + j) * 128 + 16 * wave + lq] = acc2[mt][j];
	v_mfma_f32_16x16x32_bf16 v[208:211], v[64:67], v[40:43], v[208:211]
	v_mfma_f32_16x16x32_bf16 v[212:215], v[68:71], v[40:43], v[212:215]
	global_load_dwordx4 v[40:43], v226, s[8:9] offset:3712
	ds_read_b128 v[64:67], v229 offset:2880
	ds_read_b128 v[68:71], v230 offset:2880
	s_waitcnt vmcnt(15) lgkmcnt(4)
	v_mfma_f32_16x16x32_bf16 v[208:211], v[72:75], v[44:47], v[208:211]
	v_mfma_f32_16x16x32_bf16 v[212:215], v[76:79], v[44:47], v[212:215]
	global_load_dwordx4 v[44:47], v226, s[8:9] offset:3776
	ds_read_b128 v[72:75], v229 offset:2944
	ds_read_b128 v[76:79], v230 offset:2944
	s_waitcnt vmcnt(15) lgkmcnt(4)
	v_mfma_f32_16x16x32_bf16 v[208:211], v[80:83], v[48:51], v[208:211]
	v_mfma_f32_16x16x32_bf16 v[212:215], v[84:87], v[48:51], v[212:215]
	global_load_dwordx4 v[48:51], v226, s[8:9] offset:3840
	ds_read_b128 v[80:83], v229 offset:3008
	ds_read_b128 v[84:87], v230 offset:3008
	s_waitcnt vmcnt(15) lgkmcnt(4)
	v_mfma_f32_16x16x32_bf16 v[208:211], v[64:67], v[52:55], v[208:211]
	v_mfma_f32_16x16x32_bf16 v[212:215], v[68:71], v[52:55], v[212:215]
	global_load_dwordx4 v[52:55], v226, s[8:9] offset:3904
	ds_read_b128 v[64:67], v229 offset:3072
	ds_read_b128 v[68:71], v230 offset:3072
	s_waitcnt vmcnt(15) lgkmcnt(4)
	v_mfma_f32_16x16x32_bf16 v[208:211], v[72:75], v[56:59], v[208:211]
	v_mfma_f32_16x16x32_bf16 v[212:215], v[76:79], v[56:59], v[212:215]
	global_load_dwordx4 v[56:59], v226, s[8:9] offset:3968
	ds_read_b128 v[72:75], v229 offset:3136
	ds_read_b128 v[76:79], v230 offset:3136
	s_waitcnt vmcnt(15) lgkmcnt(4)
	v_mfma_f32_16x16x32_bf16 v[208:211], v[80:83], v[60:63], v[208:211]
	v_mfma_f32_16x16x32_bf16 v[212:215], v[84:87], v[60:63], v[212:215]
	global_load_dwordx4 v[60:63], v226, s[8:9] offset:4032
	ds_read_b128 v[80:83], v229 offset:3200
	ds_read_b128 v[84:87], v230 offset:3200
	s_waitcnt vmcnt(15) lgkmcnt(4)
	v_mfma_f32_16x16x32_bf16 v[208:211], v[64:67], v[0:3], v[208:211]
	v_mfma_f32_16x16x32_bf16 v[212:215], v[68:71], v[0:3], v[212:215]
	ds_read_b128 v[64:67], v229 offset:3264
	ds_read_b128 v[68:71], v230 offset:3264
	s_waitcnt vmcnt(14) lgkmcnt(4)
	v_mfma_f32_16x16x32_bf16 v[208:211], v[72:75], v[4:7], v[208:211]
	v_mfma_f32_16x16x32_bf16 v[212:215], v[76:79], v[4:7], v[212:215]
	ds_read_b128 v[72:75], v229 offset:3328
	ds_read_b128 v[76:79], v230 offset:3328
	s_waitcnt vmcnt(13) lgkmcnt(4)
	v_mfma_f32_16x16x32_bf16 v[208:211], v[80:83], v[8:11], v[208:211]
	v_mfma_f32_16x16x32_bf16 v[212:215], v[84:87], v[8:11], v[212:215]
	ds_read_b128 v[80:83], v229 offset:3392
	ds_read_b128 v[84:87], v230 offset:3392
	s_waitcnt vmcnt(12) lgkmcnt(4)
	v_mfma_f32_16x16x32_bf16 v[208:211], v[64:67], v[12:15], v[208:211]
	v_mfma_f32_16x16x32_bf16 v[212:215], v[68:71], v[12:15], v[212:215]
	ds_read_b128 v[64:67], v229 offset:3456
	ds_read_b128 v[68:71], v230 offset:3456
	s_waitcnt vmcnt(11) lgkmcnt(4)
	v_mfma_f32_16x16x32_bf16 v[208:211], v[72:75], v[16:19], v[208:211]
	v_mfma_f32_16x16x32_bf16 v[212:215], v[76:79], v[16:19], v[212:215]
	ds_read_b128 v[72:75], v229 offset:3520
	ds_read_b128 v[76:79], v230 offset:3520
	s_waitcnt vmcnt(10) lgkmcnt(4)
	v_mfma_f32_16x16x32_bf16 v[208:211], v[80:83], v[20:23], v[208:211]
	v_mfma_f32_16x16x32_bf16 v[212:215], v[84:87], v[20:23], v[212:215]
	ds_read_b128 v[80:83], v229 offset:3584
	ds_read_b128 v[84:87], v230 offset:3584
	s_waitcnt vmcnt(9) lgkmcnt(4)
	v_mfma_f32_16x16x32_bf16 v[208:211], v[64:67], v[24:27], v[208:211]
	v_mfma_f32_16x16x32_bf16 v[212:215], v[68:71], v[24:27], v[212:215]
	ds_read_b128 v[64:67], v229 offset:3648
	ds_read_b128 v[68:71], v230 offset:3648
	s_waitcnt vmcnt(8) lgkmcnt(4)
	v_mfma_f32_16x16x32_bf16 v[208:211], v[72:75], v[28:31], v[208:211]
	v_mfma_f32_16x16x32_bf16 v[212:215], v[76:79], v[28:31], v[212:215]
	ds_read_b128 v[72:75], v229 offset:3712
	ds_read_b128 v[76:79], v230 offset:3712
	s_waitcnt vmcnt(7) lgkmcnt(4)
	v_mfma_f32_16x16x32_bf16 v[208:211], v[80:83], v[32:35], v[208:211]
	v_mfma_f32_16x16x32_bf16 v[212:215], v[84:87], v[32:35], v[212:215]
	ds_read_b128 v[80:83], v229 offset:3776
	ds_read_b128 v[84:87], v230 offset:3776
	s_waitcnt vmcnt(6) lgkmcnt(4)
	v_mfma_f32_16x16x32_bf16 v[208:211], v[64:67], v[36:39], v[208:211]
	v_mfma_f32_16x16x32_bf16 v[212:215], v[68:71], v[36:39], v[212:215]
	ds_read_b128 v[64:67], v229 offset:3840
	ds_read_b128 v[68:71], v230 offset:3840
	s_waitcnt vmcnt(5) lgkmcnt(4)
	v_mfma_f32_16x16x32_bf16 v[208:211], v[72:75], v[40:43], v[208:211]
	v_mfma_f32_16x16x32_bf16 v[212:215], v[76:79], v[40:43], v[212:215]
	ds_read_b128 v[72:75], v229 offset:3904
	ds_read_b128 v[76:79], v230 offset:3904
	s_waitcnt vmcnt(4) lgkmcnt(4)
	v_mfma_f32_16x16x32_bf16 v[208:211], v[80:83], v[44:47], v[208:211]
	v_mfma_f32_16x16x32_bf16 v[212:215], v[84:87], v[44:47], v[212:215]
	ds_read_b128 v[80:83], v229 offset:3968
	ds_read_b128 v[84:87], v230 offset:3968
	s_waitcnt vmcnt(3) lgkmcnt(4)
	v_mfma_f32_16x16x32_bf16 v[208:211], v[64:67], v[48:51], v[208:211]
	v_mfma_f32_16x16x32_bf16 v[212:215], v[68:71], v[48:51], v[212:215]
	ds_read_b128 v[64:67], v229 offset:4032
	ds_read_b128 v[68:71], v230 offset:4032
	s_waitcnt vmcnt(2) lgkmcnt(4)
	v_mfma_f32_16x16x32_bf16 v[208:211], v[72:75], v[52:55], v[208:211]
	v_mfma_f32_16x16x32_bf16 v[212:215], v[76:79], v[52:55], v[212:215]
	s_waitcnt vmcnt(1) lgkmcnt(2)
	v_mfma_f32_16x16x32_bf16 v[208:211], v[80:83], v[56:59], v[208:211]
	v_mfma_f32_16x16x32_bf16 v[212:215], v[84:87], v[56:59], v[212:215]
	s_waitcnt vmcnt(0) lgkmcnt(0)
	v_mfma_f32_16x16x32_bf16 v[208:211], v[64:67], v[60:63], v[208:211]
	v_mfma_f32_16x16x32_bf16 v[212:215], v[68:71], v[60:63], v[212:215]
	s_nop 7
	s_nop 1
	global_store_dword v227, v208, s[12:13]
	global_store_dword v227, v209, s[12:13] offset:512
	global_store_dword v227, v210, s[12:13] offset:1024
	global_store_dword v227, v211, s[12:13] offset:1536
	global_store_dword v228, v212, s[12:13]
	global_store_dword v228, v213, s[12:13] offset:512
	global_store_dword v228, v214, s[12:13] offset:1024
	global_store_dword v228, v215, s[12:13] offset:1536
	s_add_i32 s3, s3, s90
	s_cmpk_gt_i32 s3, 0xff
	s_barrier
	s_cbranch_scc0 .Lxw_tile
